# P0 off-load: w_out_a/w_in_b/w_out_b of each layer pair transposed by WGs 128-255 in the idle half-round of the A-layer in-projection (P0 item loop reused, P0 keeps only w_in_a)
# speedup vs baseline: 1.0093x; 1.0093x over previous
; #define LAS __attribute__((address_space(3)))
; DI void phase_p0(const Params& p, LAS unsigned char* lds, int gw, int NGW, int wave, int lane) {
;     LAS float* scr = (LAS float*)(lds + wave * 16896);
;     constexpr int I_INA = (D / 128) * (NA / 32), I_OUT = (D / 128) * (D / 32), I_INB = (D / 128) * (NB / 32);
;     constexpr int NITEMS = 2 * (I_INA + I_OUT + I_INB + I_OUT);
;     for (int it = gw; it < NITEMS; it += NGW) {
;         int r = it;
;         if (r < 2 * I_INA) { const int j = r / I_INA; p0_transpose_item(p.w_in_a + (size_t)j * D * NA, D, NA, (bf16_t*)(p.ws + WS_W + j * WPAIR + WO_INA), scr, r % I_INA, lane); continue; } r -= 2 * I_INA;
;         if (r < 2 * I_OUT) { const int j = r / I_OUT; p0_transpose_item(p.w_out_a + (size_t)j * D * D, D, D, (bf16_t*)(p.ws + WS_W + j * WPAIR + WO_OUTA), scr, r % I_OUT, lane); continue; } r -= 2 * I_OUT;
;         if (r < 2 * I_INB) { const int j = r / I_INB; p0_transpose_item(p.w_in_b + (size_t)j * D * NB, D, NB, (bf16_t*)(p.ws + WS_W + j * WPAIR + WO_INB), scr, r % I_INB, lane); continue; } r -= 2 * I_INB;
;         { const int j = r / I_OUT; p0_transpose_item(p.w_out_b + (size_t)j * D * D, D, D, (bf16_t*)(p.ws + WS_W + j * WPAIR + WO_OUTB), scr, r % I_OUT, lane); }
;     }
; __global__ void __launch_bounds__(NTHREADS) hybrid_fwd(Params p) {
;     ...
;         const int tid = threadIdx.x, lane = tid & 63, wave = __builtin_amdgcn_readfirstlane(tid >> 6);
;         const int G = gridDim.x, gw = blockIdx.x * NWAVES + wave, NGW = G * NWAVES;
;         if (tid < 2) bst[tid] = 0u;
;         if (blockIdx.x == 0) { for (int i = tid; i < XCD_BAR_WORDS; i += NTHREADS) barw[i] = 0u; for (int i = tid; i < 4 * 8 * 64; i += NTHREADS) ((unsigned*)(p.ws + WS_Q))[i] = 0u; }
;         phase_p0(p, lds, gw, NGW, wave, lane);
_Z10hybrid_fwd6Params:
	s_mov_b32 s100, 0
	s_movk_i32 s101, 0x11ff
	v_writelane_b32 v245, s0, 0
	v_writelane_b32 v245, s1, 1
	s_load_dwordx8 s[88:95], s[0:1], 0x40
	s_load_dword s99, s[0:1], 0x68
	s_add_u32 s6, s0, 0x68
	v_and_b32_e32 v34, 0x3ff, v0
	s_addc_u32 s7, s1, 0
	v_readfirstlane_b32 s16, v34
	v_cmp_gt_u32_e32 vcc, 2, v34
	s_and_saveexec_b64 s[8:9], vcc
	v_lshl_add_u32 v1, v34, 2, 0
	v_add_u32_e32 v1, 0x24000, v1
	v_mov_b32_e32 v2, 0
	ds_write_b32 v1, v2
	s_or_b64 exec, exec, s[8:9]
	s_waitcnt lgkmcnt(0)
	s_add_u32 s96, s94, 0x1c900000
	s_addc_u32 s97, s95, 0
	s_cmp_lg_u32 s2, 0
	s_mov_b32 s8, 0
	s_cbranch_scc1 .LBB0_14
	v_sub_u32_e32 v1, 0xd7f, v34
	v_lshrrev_b32_e32 v4, 9, v1
	v_add_u32_e32 v1, 2, v4
	v_add_u32_e32 v3, 0x200, v34
	v_mov_b32_e32 v2, v34
	v_and_b32_e32 v10, 14, v1
	v_mov_b32_e32 v5, v4
	v_mov_b32_e32 v1, v34
	s_mov_b64 s[10:11], 0
	s_mov_b32 s9, 1
	v_mov_b32_e32 v7, 0
	s_mov_b32 s12, s8
	v_mov_b64_e32 v[8:9], v[2:3]
	s_branch .LBB0_5

; #define LAS __attribute__((address_space(3)))
; DI void phase_p0(const Params& p, LAS unsigned char* lds, int gw, int NGW, int wave, int lane) {
;     LAS float* scr = (LAS float*)(lds + wave * 16896);
;     constexpr int I_INA = (D / 128) * (NA / 32), I_OUT = (D / 128) * (D / 32), I_INB = (D / 128) * (NB / 32);
;     constexpr int NITEMS = 2 * (I_INA + I_OUT + I_INB + I_OUT);
;     for (int it = gw; it < NITEMS; it += NGW) {
;         int r = it;
;         if (r < 2 * I_INA) { const int j = r / I_INA; p0_transpose_item(p.w_in_a + (size_t)j * D * NA, D, NA, (bf16_t*)(p.ws + WS_W + j * WPAIR + WO_INA), scr, r % I_INA, lane); continue; } r -= 2 * I_INA;
;         if (r < 2 * I_OUT) { const int j = r / I_OUT; p0_transpose_item(p.w_out_a + (size_t)j * D * D, D, D, (bf16_t*)(p.ws + WS_W + j * WPAIR + WO_OUTA), scr, r % I_OUT, lane); continue; } r -= 2 * I_OUT;
;         if (r < 2 * I_INB) { const int j = r / I_INB; p0_transpose_item(p.w_in_b + (size_t)j * D * NB, D, NB, (bf16_t*)(p.ws + WS_W + j * WPAIR + WO_INB), scr, r % I_INB, lane); continue; } r -= 2 * I_INB;
;         { const int j = r / I_OUT; p0_transpose_item(p.w_out_b + (size_t)j * D * D, D, D, (bf16_t*)(p.ws + WS_W + j * WPAIR + WO_OUTB), scr, r % I_OUT, lane); }
;     }
.LBB0_14:
	s_load_dwordx16 s[72:87], s[0:1], 0x0
	s_lshr_b32 s1, s16, 6
	s_lshl_b32 s0, s2, 3
	s_add_i32 s4, s1, s0
	s_lshl_b32 s0, s99, 3
	s_cmpk_gt_i32 s4, 0x11ff
	v_and_b32_e32 v1, 63, v34
	v_writelane_b32 v239, s2, 0
	s_cbranch_scc1 .LBB0_29
.Lp0_pre:
	s_mulk_i32 s1, 0x4200
	v_and_b32_e32 v4, 7, v34
	v_lshrrev_b32_e32 v6, 3, v1
	s_add_i32 s1, s1, 0
	v_lshlrev_b32_e32 v2, 2, v4
	v_lshlrev_b32_e32 v4, 4, v4
	v_mul_u32_u24_e32 v5, 0x84, v6
	v_add3_u32 v7, s1, v4, v5
	v_lshlrev_b32_e32 v4, 3, v34
	v_lshrrev_b32_e32 v8, 4, v1
	v_and_b32_e32 v4, 0x78, v4
	v_mul_u32_u24_e32 v5, 0x84, v4
	v_lshlrev_b32_e32 v9, 2, v8
	v_add3_u32 v9, s1, v5, v9
	s_lshl_b32 s1, s4, 1
	s_mov_b32 s9, 0
	v_mov_b32_e32 v3, 0
	v_or_b32_e32 v10, 4, v8
	v_or_b32_e32 v11, 8, v8
	v_or_b32_e32 v12, 12, v8
	v_or_b32_e32 v13, 16, v8
	v_or_b32_e32 v14, 20, v8
	v_or_b32_e32 v15, 24, v8
	v_or_b32_e32 v16, 28, v8
	s_addk_i32 s1, 0x8c00
	s_lshl_b32 s5, s0, 1
	s_lshl_b32 s20, s4, 5
	s_lshl_b32 s21, s0, 5
	s_mov_b32 s22, 0x10000
	s_mov_b32 s23, 0x20000
	s_mov_b32 s24, 0x30000
	s_mov_b32 s25, 0x40000
	s_mov_b32 s26, 0x50000
	s_mov_b32 s27, 0x60000
	s_mov_b32 s28, 0x70000
	s_mov_b32 s29, 0x80000
	s_mov_b32 s30, 0x90000
	s_mov_b32 s31, 0xa0000
	s_mov_b32 s33, 0xb0000
	s_mov_b32 s34, 0xc0000
	s_mov_b32 s35, 0xd0000
	s_mov_b32 s36, 0xe0000
	s_mov_b32 s37, 0xf0000
	v_add_u32_e32 v17, 0x420, v7
	v_add_u32_e32 v18, 0x428, v7
	v_add_u32_e32 v19, 0x840, v7
	v_add_u32_e32 v20, 0x848, v7
	v_add_u32_e32 v21, 0xc60, v7
	v_add_u32_e32 v22, 0xc68, v7
	v_add_u32_e32 v23, 0x1080, v7
	v_add_u32_e32 v24, 0x1088, v7
	v_add_u32_e32 v25, 0x14a0, v7
	v_add_u32_e32 v26, 0x14a8, v7
	v_add_u32_e32 v27, 0x18c0, v7
	v_add_u32_e32 v28, 0x18c8, v7
	v_add_u32_e32 v29, 0x1ce0, v7
	v_add_u32_e32 v30, 0x1ce8, v7
	v_add_u32_e32 v31, 0x2100, v7
	v_add_u32_e32 v32, 0x2108, v7
	v_add_u32_e32 v33, 0x2520, v7
	v_add_u32_e32 v35, 0x2528, v7
	v_add_u32_e32 v36, 0x2940, v7
	v_add_u32_e32 v37, 0x2948, v7
	v_add_u32_e32 v38, 0x2d60, v7
	v_add_u32_e32 v39, 0x2d68, v7
	v_add_u32_e32 v40, 0x3180, v7
	v_add_u32_e32 v41, 0x3188, v7
	v_add_u32_e32 v42, 0x35a0, v7
	v_add_u32_e32 v43, 0x35a8, v7
	v_add_u32_e32 v44, 0x39c0, v7
	v_add_u32_e32 v45, 0x39c8, v7
	v_add_u32_e32 v46, 0x3de0, v7
	v_add_u32_e32 v47, 0x3de8, v7
	s_mov_b64 s[10:11], 0x3a00000
	s_mov_b32 s38, 0x100000
	s_mov_b32 s39, 0x140000
	s_mov_b32 s40, 0x180000
	s_mov_b32 s41, 0x1c0000
	s_mov_b32 s42, 0x200000
	s_mov_b32 s43, 0x240000
	s_mov_b32 s44, 0x280000
	s_mov_b32 s45, 0x2c0000
	s_mov_b32 s46, 0x300000
	s_mov_b32 s47, 0x340000
	s_mov_b32 s48, 0x380000
	s_mov_b32 s49, 0x3c0000
	s_mov_b64 s[12:13], 0x1a00000
	s_mov_b64 s[14:15], 0x1200000
	s_mov_b32 s50, 0x24000
	s_mov_b32 s51, 0x48000
	s_mov_b32 s52, 0x6c000
	s_mov_b32 s53, 0xb4000
	s_mov_b32 s54, 0xd8000
	s_mov_b32 s55, 0xfc000
	s_mov_b32 s56, 0x120000
	s_mov_b32 s57, 0x144000
	s_mov_b32 s58, 0x168000
	s_mov_b32 s59, 0x18c000
	s_mov_b32 s60, 0x1b0000
	s_mov_b32 s61, 0x1d4000
	s_mov_b32 s62, 0x1f8000
	s_mov_b32 s63, 0x21c000
	v_lshlrev_b32_e32 v2, 2, v2
	v_lshlrev_b32_e32 v4, 1, v4
	v_add_u32_e32 v48, 0x200, v9
	s_mov_b32 s64, s4
	s_branch .LBB0_17
.LBB0_16:
	s_add_i32 s64, s64, s0
	s_add_i32 s1, s1, s5
	s_add_i32 s20, s20, s21
	s_cmp_gt_i32 s64, s101
	s_cbranch_scc1 .LBB0_29

; DI void phase_p0(const Params& p, LAS unsigned char* lds, int gw, int NGW, int wave, int lane) {
;     ...
;     bf16_t* hb = (bf16_t*)(p.ws + WS_HB);
;     { unsigned char* zb = p.ws + WS_Z;
;       for (size_t i = (size_t)(gw * 64 + lane) * 16; i < (size_t)(18 + 32) << 17; i += (size_t)NGW * 64 * 16) {
;           unsigned char* dst = i < ((size_t)18 << 17) ? zb + ((size_t)(64 * 18) << 17) + i : zb + ((size_t)(64 * 32) << 17) + (i - ((size_t)18 << 17));
;           *(u32x4*)dst = (u32x4){0u, 0u, 0u, 0u}; } }
.LBB0_29:
	s_cmpk_lg_i32 s101, 0x11ff
	s_cbranch_scc1 .Lslot_ret
	v_lshl_or_b32 v2, s4, 6, v1
	v_ashrrev_i32_e32 v3, 31, v2
	v_lshlrev_b64 v[2:3], 4, v[2:3]
	s_mov_b64 s[8:9], 0x640000
	v_cmp_gt_u64_e32 vcc, s[8:9], v[2:3]
	s_and_saveexec_b64 s[8:9], vcc
	s_cbranch_execz .LBB0_32
	s_ashr_i32 s1, s0, 31
	v_mov_b32_e32 v5, 0
	s_lshl_b64 s[10:11], s[0:1], 10
	s_mov_b64 s[12:13], 0
	s_mov_b64 s[14:15], 0x240000
	v_mov_b32_e32 v6, 0x1c2c0000
	v_mov_b32_e32 v7, 0x15500000
	v_mov_b32_e32 v8, v5
	v_mov_b32_e32 v9, v5
	v_mov_b32_e32 v10, v5
	v_mov_b32_e32 v11, v5
	s_mov_b64 s[16:17], 0x63ffff

; #define PHASE_IDS() int lane = lane_id_fresh(); int wave = wave_s; asm volatile("" : "+s"(wave)); \
;         int bid = blockIdx.x; asm volatile("" : "+s"(bid)); int G = gridDim.x; asm volatile("" : "+s"(G)); \
;         const int tid = wave * 64 + lane, gw = bid * NWAVES + wave, NGW = G * NWAVES; (void)tid; (void)gw; (void)NGW
; DI void phase_p0(const Params& p, LAS unsigned char* lds, int gw, int NGW, int wave, int lane) {
;     ...
;     for (int it = gw; it < NITEMS; it += NGW) {
;         int r = it;
;         if (r < 2 * I_INA) { const int j = r / I_INA; p0_transpose_item(p.w_in_a + (size_t)j * D * NA, D, NA, (bf16_t*)(p.ws + WS_W + j * WPAIR + WO_INA), scr, r % I_INA, lane); continue; } r -= 2 * I_INA;
;         if (r < 2 * I_OUT) { const int j = r / I_OUT; p0_transpose_item(p.w_out_a + (size_t)j * D * D, D, D, (bf16_t*)(p.ws + WS_W + j * WPAIR + WO_OUTA), scr, r % I_OUT, lane); continue; } r -= 2 * I_OUT;
;         if (r < 2 * I_INB) { const int j = r / I_INB; p0_transpose_item(p.w_in_b + (size_t)j * D * NB, D, NB, (bf16_t*)(p.ws + WS_W + j * WPAIR + WO_INB), scr, r % I_INB, lane); continue; } r -= 2 * I_INB;
;         { const int j = r / I_OUT; p0_transpose_item(p.w_out_b + (size_t)j * D * D, D, D, (bf16_t*)(p.ws + WS_W + j * WPAIR + WO_OUTB), scr, r % I_OUT, lane); }
;     }
; __global__ void __launch_bounds__(NTHREADS) hybrid_fwd(Params p) {
;     ...
;             PHASE_IDS();
;             const int N = isA ? NA : NB;
;             const bf16_t* wt = isA ? (const bf16_t*)(p.ws + WS_W + j * WPAIR + WO_INA) : (const bf16_t*)(p.ws + WS_W + j * WPAIR + WO_INB);
;             pg8::StaticOrder S; S.init(SEQ, N, G, bid);
;             pg8::Gemm g{hb, wt, SEQ, N, D, D, 0};
;             pg8::EpiBf16 E{z, 0, N / 256}; pg8::gemm_phase<pg8::EpiBf16>(lds, g, S, E, tid);
;             meta_gemm<false>(hb + (size_t)SEQ * D, D, wt, N, z, 0, N / 256, lds, bid, G, wave, lane);
.LBB0_74:
	s_bitcmp1_b32 s20, 0
	s_cbranch_scc1 .Lslot_skip
	v_readlane_b32 s4, v239, 0
	s_cmpk_lt_u32 s4, 0x80
	s_cbranch_scc1 .Lslot_skip
	s_waitcnt vmcnt(0) lgkmcnt(0)
	s_barrier
	v_writelane_b32 v246, s0, 0
	v_writelane_b32 v246, s1, 1
	v_writelane_b32 v246, s2, 2
	v_writelane_b32 v246, s3, 3
	v_writelane_b32 v246, s4, 4
	v_writelane_b32 v246, s5, 5
	v_writelane_b32 v246, s6, 6
	v_writelane_b32 v246, s7, 7
	v_writelane_b32 v246, s8, 8
	v_writelane_b32 v246, s9, 9
	v_writelane_b32 v246, s10, 10
	v_writelane_b32 v246, s11, 11
	v_writelane_b32 v246, s12, 12
	v_writelane_b32 v246, s13, 13
	v_writelane_b32 v246, s14, 14
	v_writelane_b32 v246, s15, 15
	v_writelane_b32 v246, s16, 16
	v_writelane_b32 v246, s17, 17
	v_writelane_b32 v246, s18, 18
	v_writelane_b32 v246, s19, 19
	v_writelane_b32 v246, s20, 20
	v_writelane_b32 v246, s21, 21
	v_writelane_b32 v246, s22, 22
	v_writelane_b32 v246, s23, 23
	v_writelane_b32 v246, s24, 24
	v_writelane_b32 v246, s25, 25
	v_writelane_b32 v246, s26, 26
	v_writelane_b32 v246, s27, 27
	v_writelane_b32 v246, s28, 28
	v_writelane_b32 v246, s29, 29
	v_writelane_b32 v246, s30, 30
	v_writelane_b32 v246, s31, 31
	v_writelane_b32 v246, s32, 32
	v_writelane_b32 v246, s33, 33
	v_writelane_b32 v246, s34, 34
	v_writelane_b32 v246, s35, 35
	v_writelane_b32 v246, s36, 36
	v_writelane_b32 v246, s37, 37
	v_writelane_b32 v246, s38, 38
	v_writelane_b32 v246, s39, 39
	v_writelane_b32 v246, s40, 40
	v_writelane_b32 v246, s41, 41
	v_writelane_b32 v246, s42, 42
	v_writelane_b32 v246, s43, 43
	v_writelane_b32 v246, s44, 44
	v_writelane_b32 v246, s45, 45
	v_writelane_b32 v246, s46, 46
	v_writelane_b32 v246, s47, 47
	v_writelane_b32 v246, s48, 48
	v_writelane_b32 v246, s49, 49
	v_writelane_b32 v246, s50, 50
	v_writelane_b32 v246, s51, 51
	v_writelane_b32 v246, s52, 52
	v_writelane_b32 v246, s53, 53
	v_writelane_b32 v246, s54, 54
	v_writelane_b32 v246, s55, 55
	v_writelane_b32 v246, s56, 56
	v_writelane_b32 v246, s57, 57
	v_writelane_b32 v246, s58, 58
	v_writelane_b32 v246, s59, 59
	v_writelane_b32 v246, s60, 60
	v_writelane_b32 v246, s61, 61
	v_writelane_b32 v246, s62, 62
	v_writelane_b32 v246, s63, 63
	v_writelane_b32 v247, s64, 0
	v_writelane_b32 v247, s65, 1
	v_writelane_b32 v247, s66, 2
	v_writelane_b32 v247, s67, 3
	v_writelane_b32 v247, s68, 4
	v_writelane_b32 v247, s69, 5
	v_writelane_b32 v247, s70, 6
	v_writelane_b32 v247, s71, 7
	v_writelane_b32 v247, s72, 8
	v_writelane_b32 v247, s73, 9
	v_writelane_b32 v247, s74, 10
	v_writelane_b32 v247, s75, 11
	v_writelane_b32 v247, s76, 12
	v_writelane_b32 v247, s77, 13
	v_writelane_b32 v247, s78, 14
	v_writelane_b32 v247, s79, 15
	v_writelane_b32 v247, s80, 16
	v_writelane_b32 v247, s81, 17
	v_writelane_b32 v247, s82, 18
	v_writelane_b32 v247, s83, 19
	v_writelane_b32 v247, s84, 20
	v_writelane_b32 v247, s85, 21
	v_writelane_b32 v247, s86, 22
	v_writelane_b32 v247, s87, 23
	v_writelane_b32 v247, s88, 24
	v_writelane_b32 v247, s89, 25
	v_writelane_b32 v247, s90, 26
	v_writelane_b32 v247, s91, 27
	v_writelane_b32 v247, s92, 28
	v_writelane_b32 v247, s93, 29
	v_writelane_b32 v247, s94, 30
	v_writelane_b32 v247, s95, 31
	v_writelane_b32 v247, s96, 32
	v_writelane_b32 v247, s97, 33
	v_writelane_b32 v247, s98, 34
	v_writelane_b32 v247, s99, 35
	v_writelane_b32 v247, vcc_lo, 36
	v_writelane_b32 v247, vcc_hi, 37
	v_readlane_b32 s89, v239, 0
	v_readlane_b32 s91, v239, 1
	v_readlane_b32 s92, v245, 0
	v_readlane_b32 s93, v245, 1
	s_lshr_b32 s90, s20, 1
	s_sub_i32 s89, s89, 0x80
	s_lshl_b32 s89, s89, 3
	s_add_i32 s89, s89, s91
	s_nop 4
	s_load_dwordx16 s[72:87], s[92:93], 0x0
	s_mov_b32 s88, 0
	s_waitcnt lgkmcnt(0)
.Lslot_next:
	s_cmp_eq_u32 s88, 3
	s_cbranch_scc1 .Lslot_done
	s_lshl_b32 s4, s90, 10
	s_addk_i32 s4, 0x1200
	s_add_i32 s101, s4, 0x3ff
	s_cmp_eq_u32 s88, 1
	s_cbranch_scc0 .Lslot_r2
	s_lshl_b32 s4, s90, 12
	s_addk_i32 s4, 0x1a00
	s_add_i32 s101, s4, 0xfff
.Lslot_r2:
	s_cmp_eq_u32 s88, 2
	s_cbranch_scc0 .Lslot_go
	s_lshl_b32 s4, s90, 10
	s_addk_i32 s4, 0x3a00
	s_add_i32 s101, s4, 0x3ff
.Lslot_go:
	s_add_i32 s88, s88, 1
	s_add_i32 s4, s4, s89
	s_movk_i32 s0, 0x400
	s_mov_b32 s1, s91
	v_mbcnt_lo_u32_b32 v1, -1, 0
	v_mbcnt_hi_u32_b32 v1, -1, v1
	v_lshl_add_u32 v34, s91, 6, v1
	s_branch .Lp0_pre

; #define GSYNC() xcd_barrier(xb, wave_s)
; #define PHASE_IDS() int lane = lane_id_fresh(); int wave = wave_s; asm volatile("" : "+s"(wave)); \
;         int bid = blockIdx.x; asm volatile("" : "+s"(bid)); int G = gridDim.x; asm volatile("" : "+s"(G)); \
;         const int tid = wave * 64 + lane, gw = bid * NWAVES + wave, NGW = G * NWAVES; (void)tid; (void)gw; (void)NGW
; __global__ void __launch_bounds__(NTHREADS) hybrid_fwd(Params p) {
;     ...
;             PHASE_IDS();
;             const int N = isA ? NA : NB;
;             const bf16_t* wt = isA ? (const bf16_t*)(p.ws + WS_W + j * WPAIR + WO_INA) : (const bf16_t*)(p.ws + WS_W + j * WPAIR + WO_INB);
;             pg8::StaticOrder S; S.init(SEQ, N, G, bid);
;             pg8::Gemm g{hb, wt, SEQ, N, D, D, 0};
;             pg8::EpiBf16 E{z, 0, N / 256}; pg8::gemm_phase<pg8::EpiBf16>(lds, g, S, E, tid);
;             meta_gemm<false>(hb + (size_t)SEQ * D, D, wt, N, z, 0, N / 256, lds, bid, G, wave, lane);
;         }
;         GSYNC();
.Lslot_done:
	s_waitcnt vmcnt(0) lgkmcnt(0)
	v_readlane_b32 s0, v246, 0
	v_readlane_b32 s1, v246, 1
	v_readlane_b32 s2, v246, 2
	v_readlane_b32 s3, v246, 3
	v_readlane_b32 s4, v246, 4
	v_readlane_b32 s5, v246, 5
	v_readlane_b32 s6, v246, 6
	v_readlane_b32 s7, v246, 7
	v_readlane_b32 s8, v246, 8
	v_readlane_b32 s9, v246, 9
	v_readlane_b32 s10, v246, 10
	v_readlane_b32 s11, v246, 11
	v_readlane_b32 s12, v246, 12
	v_readlane_b32 s13, v246, 13
	v_readlane_b32 s14, v246, 14
	v_readlane_b32 s15, v246, 15
	v_readlane_b32 s16, v246, 16
	v_readlane_b32 s17, v246, 17
	v_readlane_b32 s18, v246, 18
	v_readlane_b32 s19, v246, 19
	v_readlane_b32 s20, v246, 20
	v_readlane_b32 s21, v246, 21
	v_readlane_b32 s22, v246, 22
	v_readlane_b32 s23, v246, 23
	v_readlane_b32 s24, v246, 24
	v_readlane_b32 s25, v246, 25
	v_readlane_b32 s26, v246, 26
	v_readlane_b32 s27, v246, 27
	v_readlane_b32 s28, v246, 28
	v_readlane_b32 s29, v246, 29
	v_readlane_b32 s30, v246, 30
	v_readlane_b32 s31, v246, 31
	v_readlane_b32 s32, v246, 32
	v_readlane_b32 s33, v246, 33
	v_readlane_b32 s34, v246, 34
	v_readlane_b32 s35, v246, 35
	v_readlane_b32 s36, v246, 36
	v_readlane_b32 s37, v246, 37
	v_readlane_b32 s38, v246, 38
	v_readlane_b32 s39, v246, 39
	v_readlane_b32 s40, v246, 40
	v_readlane_b32 s41, v246, 41
	v_readlane_b32 s42, v246, 42
	v_readlane_b32 s43, v246, 43
	v_readlane_b32 s44, v246, 44
	v_readlane_b32 s45, v246, 45
	v_readlane_b32 s46, v246, 46
	v_readlane_b32 s47, v246, 47
	v_readlane_b32 s48, v246, 48
	v_readlane_b32 s49, v246, 49
	v_readlane_b32 s50, v246, 50
	v_readlane_b32 s51, v246, 51
	v_readlane_b32 s52, v246, 52
	v_readlane_b32 s53, v246, 53
	v_readlane_b32 s54, v246, 54
	v_readlane_b32 s55, v246, 55
	v_readlane_b32 s56, v246, 56
	v_readlane_b32 s57, v246, 57
	v_readlane_b32 s58, v246, 58
	v_readlane_b32 s59, v246, 59
	v_readlane_b32 s60, v246, 60
	v_readlane_b32 s61, v246, 61
	v_readlane_b32 s62, v246, 62
	v_readlane_b32 s63, v246, 63
	v_readlane_b32 s64, v247, 0
	v_readlane_b32 s65, v247, 1
	v_readlane_b32 s66, v247, 2
	v_readlane_b32 s67, v247, 3
	v_readlane_b32 s68, v247, 4
	v_readlane_b32 s69, v247, 5
	v_readlane_b32 s70, v247, 6
	v_readlane_b32 s71, v247, 7
	v_readlane_b32 s72, v247, 8
	v_readlane_b32 s73, v247, 9
	v_readlane_b32 s74, v247, 10
	v_readlane_b32 s75, v247, 11
	v_readlane_b32 s76, v247, 12
	v_readlane_b32 s77, v247, 13
	v_readlane_b32 s78, v247, 14
	v_readlane_b32 s79, v247, 15
	v_readlane_b32 s80, v247, 16
	v_readlane_b32 s81, v247, 17
	v_readlane_b32 s82, v247, 18
	v_readlane_b32 s83, v247, 19
	v_readlane_b32 s84, v247, 20
	v_readlane_b32 s85, v247, 21
	v_readlane_b32 s86, v247, 22
	v_readlane_b32 s87, v247, 23
	v_readlane_b32 s88, v247, 24
	v_readlane_b32 s89, v247, 25
	v_readlane_b32 s90, v247, 26
	v_readlane_b32 s91, v247, 27
	v_readlane_b32 s92, v247, 28
	v_readlane_b32 s93, v247, 29
	v_readlane_b32 s94, v247, 30
	v_readlane_b32 s95, v247, 31
	v_readlane_b32 s96, v247, 32
	v_readlane_b32 s97, v247, 33
	v_readlane_b32 s98, v247, 34
	v_readlane_b32 s99, v247, 35
	v_readlane_b32 vcc_lo, v247, 36
	v_readlane_b32 vcc_hi, v247, 37
	v_mov_b32_e32 v1, 0
	s_nop 4
